# HGRN loops: cumulative log-decay kept in log2 units (drops 19 pre-exp multiplies), add_dpp rmsnorm reduction, consolidated readout waits, dead token-0 chain removed
# baseline (speedup 1.0000x reference)
; #define LAS __attribute__((address_space(3)))
; __device__ __forceinline__ unsigned cvt_pk_bf16(float lo, float hi) { unsigned r; asm volatile("v_cvt_pk_bf16_f32 %0, %1, %2" : "=v"(r) : "v"(lo), "v"(hi)); return r; }
; __device__ __forceinline__ float bf2f(unsigned short b) { return __uint_as_float(((unsigned)b) << 16); }
; template <bool FULL>
; __device__ __forceinline__ void hgrn_item(LAS unsigned char* lds, const bf16_t* P, bf16_t* AB, int L, int hd, const float* lbv, const float* anorm, const float* S0, const float* Dd, int ns, float* Sout, float* Dout) {
;     ...
;         {
;             float run = 0.f;
; #pragma unroll
;             for (int i = 0; i < 4; ++i) { float z = bf2f(zc[i]); z = fminf(fmaxf(z, -30.f), 30.f); const float e = __expf(-z), sg = __builtin_amdgcn_rcpf(1.f + e), sn = e * sg;
;                 const float f = lb + oml * sg; run += __builtin_amdgcn_logf(f) * 0.69314718056f; cs[i] = run; kk[i] = oml * sn; qv[i] = bf2f(qc[i]); }
;             qsum[tq * 128 + k] = run;
;         }
;         __syncthreads();
;         {
;             float pre = 0.f, tot = 0.f;
; #pragma unroll
;             for (int j = 0; j < 4; ++j) { const float v = qsum[j * 128 + k]; tot += v; pre += (j < tq) ? v : 0.f; }
;             btot += tot;
;             float kh[4];
; #pragma unroll
;             for (int i = 0; i < 4; ++i) { const float b = pre + cs[i]; const float qt = qv[i] * __expf(b), kt = kk[i] * __expf(fminf(-b, 80.f)); kh[i] = kk[i] * __expf(tot - b);
;                 Qt[(4 * tq + i) * 136 + k] = (bf16_t)(cvt_pk_bf16(qt, 0.f) & 0xffffu); Kt[(4 * tq + i) * 136 + k] = (bf16_t)(cvt_pk_bf16(kt, 0.f) & 0xffffu); }
;             u32x2 kp; kp.x = cvt_pk_bf16(kh[0], kh[1]); kp.y = cvt_pk_bf16(kh[2], kh[3]);
;             *(LAS u32x2*)(KhT + k * 20 + 4 * tq) = kp;
;             if (tq == 0) dvec[k] = __expf(tot);
.LBB0_227:
	s_or_b64 exec, exec, s[4:5]
	v_lshlrev_b32_e32 v68, 16, v68
	v_max_f32_e32 v68, v68, v68
	v_med3_f32 v68, v68, s29, v225
	v_lshlrev_b32_e32 v72, 16, v72
	v_mul_f32_e32 v68, 0xbfb8aa3b, v68
	v_max_f32_e32 v72, v72, v72
	v_lshlrev_b32_e32 v70, 16, v70
	v_exp_f32_e32 v68, v68
	v_med3_f32 v72, v72, s29, v225
	v_max_f32_e32 v70, v70, v70
	v_mul_f32_e32 v72, 0xbfb8aa3b, v72
	v_med3_f32 v70, v70, s29, v225
	v_lshlrev_b32_e32 v47, 16, v47
	v_exp_f32_e32 v72, v72
	v_mul_f32_e32 v70, 0xbfb8aa3b, v70
	v_max_f32_e32 v47, v47, v47
	v_exp_f32_e32 v70, v70
	v_add_f32_e32 v69, 1.0, v68
	v_med3_f32 v47, v47, s29, v225
	v_rcp_f32_e32 v69, v69
	v_mul_f32_e32 v47, 0xbfb8aa3b, v47
	v_exp_f32_e32 v47, v47
	v_add_f32_e32 v73, 1.0, v72
	v_rcp_f32_e32 v73, v73
	v_add_f32_e32 v71, 1.0, v70
	v_rcp_f32_e32 v71, v71
	v_mul_f32_e32 v68, v68, v69
	v_mul_f32_e32 v78, v55, v68
	v_add_f32_e32 v68, 1.0, v47
	v_rcp_f32_e32 v68, v68
	v_mul_f32_e32 v72, v72, v73
	v_fma_f32 v73, v55, v73, v53
	v_log_f32_e32 v73, v73
	v_mul_f32_e32 v70, v70, v71
	v_fma_f32 v71, v55, v71, v53
	v_log_f32_e32 v71, v71
	v_fma_f32 v69, v55, v69, v53
	v_log_f32_e32 v69, v69
	v_mul_f32_e32 v47, v47, v68
	v_fma_f32 v68, v55, v68, v53
	v_log_f32_e32 v68, v68
	v_add_f32_e32 v75, v71, v73
	v_mul_f32_e32 v79, v55, v47
	v_add_f32_e32 v47, v69, v75
	v_add_f32_e32 v81, v68, v47
	ds_write_b32 v54, v81 offset:19456
	s_waitcnt lgkmcnt(0)
	s_barrier
	ds_read2st64_b32 v[68:69], v49 offset0:76 offset1:78
	ds_read2st64_b32 v[128:129], v49 offset0:80 offset1:82
	v_mul_f32_e32 v76, v55, v70
	v_mul_f32_e32 v72, v55, v72
	s_waitcnt lgkmcnt(1)
	v_add_f32_e32 v46, 0, v68
	v_cndmask_b32_e64 v68, 0, v46, s[46:47]
	v_add_f32_e32 v46, v46, v69
	v_cndmask_b32_e64 v69, 0, v69, s[44:45]
	v_add_f32_e32 v70, v68, v69
	s_waitcnt lgkmcnt(0)
	v_mov_b32_e32 v68, v128
	v_mov_b32_e32 v69, v129
	v_add_f32_e32 v46, v46, v68
	v_cndmask_b32_e64 v68, 0, v68, s[42:43]
	v_add_f32_e32 v68, v70, v68
	v_cndmask_b32_e64 v70, 0, v69, s[40:41]
	v_add_f32_e32 v71, v68, v70
	v_add_f32_e32 v68, v73, v71
	v_mov_b32_e32 v70, v69
	v_pk_add_f32 v[46:47], v[46:47], v[70:71]
	v_sub_f32_e32 v68, v46, v68
	v_exp_f32_e32 v68, v68
	v_add_f32_e32 v69, v75, v71
	v_mul_f32_e32 v68, v72, v68
	v_sub_f32_e32 v69, v46, v69
	v_exp_f32_e32 v69, v69
	v_sub_f32_e32 v47, v46, v47
	v_add_f32_e32 v67, v81, v71
	v_sub_f32_e32 v67, v46, v67
	v_exp_f32_e32 v47, v47
	v_exp_f32_e32 v67, v67
	v_mul_f32_e32 v69, v76, v69
	v_mul_f32_e32 v47, v78, v47
	v_mul_f32_e32 v67, v79, v67
	v_cvt_pk_bf16_f32 v68, v68, v69
	v_cvt_pk_bf16_f32 v69, v47, v67
	ds_write_b64 v52, v[68:69] offset:8704
	s_and_saveexec_b64 s[4:5], s[38:39]
	s_cbranch_execz .LBB0_229
	v_exp_f32_e32 v47, v46
	ds_write_b32 v49, v47 offset:18944

; #define LAS __attribute__((address_space(3)))
; __device__ __forceinline__ unsigned cvt_pk_bf16(float lo, float hi) { unsigned r; asm volatile("v_cvt_pk_bf16_f32 %0, %1, %2" : "=v"(r) : "v"(lo), "v"(hi)); return r; }
; __device__ __forceinline__ float bf2f(unsigned short b) { return __uint_as_float(((unsigned)b) << 16); }
; template <bool FULL>
; __device__ __forceinline__ void hgrn_item(LAS unsigned char* lds, const bf16_t* P, bf16_t* AB, int L, int hd, const float* lbv, const float* anorm, const float* S0, const float* Dd, int ns, float* Sout, float* Dout) {
;     ...
;         float cs[4], kk[4], qv[4];
;         {
;             float run = 0.f;
; #pragma unroll
;             for (int i = 0; i < 4; ++i) { float z = bf2f(zc[i]); z = fminf(fmaxf(z, -30.f), 30.f); const float e = __expf(-z), sg = __builtin_amdgcn_rcpf(1.f + e), sn = e * sg;
;                 const float f = lb + oml * sg; run += __builtin_amdgcn_logf(f) * 0.69314718056f; cs[i] = run; kk[i] = oml * sn; qv[i] = bf2f(qc[i]); }
;             qsum[tq * 128 + k] = run;
;         }
;         __syncthreads();
;         {
;             float pre = 0.f, tot = 0.f;
; #pragma unroll
;             for (int j = 0; j < 4; ++j) { const float v = qsum[j * 128 + k]; tot += v; pre += (j < tq) ? v : 0.f; }
;             btot += tot;
;             float kh[4];
; #pragma unroll
;             for (int i = 0; i < 4; ++i) { const float b = pre + cs[i]; const float qt = qv[i] * __expf(b), kt = kk[i] * __expf(fminf(-b, 80.f)); kh[i] = kk[i] * __expf(tot - b);
;                 Qt[(4 * tq + i) * 136 + k] = (bf16_t)(cvt_pk_bf16(qt, 0.f) & 0xffffu); Kt[(4 * tq + i) * 136 + k] = (bf16_t)(cvt_pk_bf16(kt, 0.f) & 0xffffu); }
;             u32x2 kp; kp.x = cvt_pk_bf16(kh[0], kh[1]); kp.y = cvt_pk_bf16(kh[2], kh[3]);
;             *(LAS u32x2*)(KhT + k * 20 + 4 * tq) = kp;
;             if (tq == 0) dvec[k] = __expf(tot);
.LBB0_233:
	v_mul_f32_e32 v48, 0x3f317218, v48
	s_waitcnt vmcnt(7)
	v_lshlrev_b32_e32 v36, 16, v66
	v_max_f32_e32 v36, v36, v36
	v_med3_f32 v36, v36, s29, v225
	v_mul_f32_e32 v36, 0xbfb8aa3b, v36
	v_exp_f32_e32 v36, v36
	s_waitcnt vmcnt(6)
	v_lshlrev_b32_e32 v57, 16, v65
	s_waitcnt vmcnt(4)
	v_lshlrev_b32_e32 v62, 16, v62
	s_waitcnt vmcnt(2)
	v_lshlrev_b32_e32 v60, 16, v60
	v_add_f32_e32 v37, 1.0, v36
	v_rcp_f32_e32 v37, v37
	s_nop 0
	v_mul_f32_e32 v36, v36, v37
	v_mul_f32_e32 v56, v55, v36
	v_lshlrev_b32_e32 v36, 16, v64
	v_max_f32_e32 v36, v36, v36
	v_med3_f32 v36, v36, s29, v225
	v_fma_f32 v37, v55, v37, v53
	v_mul_f32_e32 v36, 0xbfb8aa3b, v36
	v_log_f32_e32 v37, v37
	v_exp_f32_e32 v36, v36
	v_fma_f32 v44, v37, s30, 0
	v_add_f32_e32 v37, 1.0, v36
	v_rcp_f32_e32 v37, v37
	s_nop 0
	v_mul_f32_e32 v36, v36, v37
	v_mul_f32_e32 v64, v55, v36
	v_lshlrev_b32_e32 v36, 16, v63
	v_max_f32_e32 v36, v36, v36
	v_med3_f32 v36, v36, s29, v225
	v_fma_f32 v37, v55, v37, v53
	v_mul_f32_e32 v36, 0xbfb8aa3b, v36
	v_log_f32_e32 v37, v37
	v_exp_f32_e32 v36, v36
	v_fmamk_f32 v58, v37, 0x3f317218, v44
	v_add_f32_e32 v37, 1.0, v36
	v_rcp_f32_e32 v37, v37
	s_nop 0
	v_mul_f32_e32 v36, v36, v37
	v_mul_f32_e32 v63, v55, v36
	s_waitcnt vmcnt(1)
	v_lshlrev_b32_e32 v36, 16, v61
	v_max_f32_e32 v36, v36, v36
	v_med3_f32 v36, v36, s29, v225
	v_mul_f32_e32 v36, 0xbfb8aa3b, v36
	v_exp_f32_e32 v36, v36
	v_fma_f32 v37, v55, v37, v53
	v_log_f32_e32 v37, v37
	v_add_f32_e32 v42, 1.0, v36
	v_rcp_f32_e32 v42, v42
	v_fmamk_f32 v37, v37, 0x3f317218, v58
	v_fmac_f32_e32 v53, v55, v42
	v_mul_f32_e32 v36, v36, v42
	v_log_f32_e32 v42, v53
	v_mul_f32_e32 v53, v55, v36
	s_waitcnt vmcnt(0)
	v_lshlrev_b32_e32 v55, 16, v59
	v_fmamk_f32 v59, v42, 0x3f317218, v37
	ds_write_b32 v54, v59 offset:19456
	s_waitcnt lgkmcnt(0)
	s_barrier
	ds_read2st64_b32 v[42:43], v49 offset0:76 offset1:78
	s_waitcnt lgkmcnt(0)
	v_add_f32_e32 v36, 0, v42
	v_cndmask_b32_e64 v42, 0, v36, s[46:47]
	v_add_f32_e32 v36, v36, v43
	v_cndmask_b32_e64 v43, 0, v43, s[44:45]
	v_add_f32_e32 v45, v42, v43
	ds_read2st64_b32 v[42:43], v49 offset0:80 offset1:82
	s_waitcnt lgkmcnt(0)
	v_add_f32_e32 v36, v36, v42
	v_cndmask_b32_e64 v42, 0, v42, s[42:43]
	v_add_f32_e32 v42, v45, v42
	v_cndmask_b32_e64 v45, 0, v43, s[40:41]
	v_add_f32_e32 v45, v42, v45
	v_add_f32_e32 v42, v44, v45
	v_mul_f32_e32 v44, 0x3fb8aa3b, v42
	v_exp_f32_e32 v44, v44
	s_nop 0
	v_mul_f32_e32 v54, v44, v57
	v_min_f32_e64 v44, -v42, s31
	v_mul_f32_e32 v44, 0x3fb8aa3b, v44
	v_exp_f32_e32 v44, v44
	s_nop 0
	v_mul_f32_e32 v57, v56, v44
	v_mov_b32_e32 v44, v43
	v_cvt_pk_bf16_f32 v43, v54, v195
	ds_write_b16 v51, v43
	v_cvt_pk_bf16_f32 v43, v57, v195
	ds_write_b16 v51, v43 offset:4352
	v_add_f32_e32 v43, v58, v45
	v_pk_add_f32 v[36:37], v[36:37], v[44:45]
	v_mul_f32_e32 v44, 0x3fb8aa3b, v43
	v_exp_f32_e32 v44, v44
	v_min_f32_e64 v54, -v43, s31
	v_mul_f32_e32 v54, 0x3fb8aa3b, v54
	v_exp_f32_e32 v54, v54
	v_mul_f32_e32 v44, v44, v62
	v_cvt_pk_bf16_f32 v44, v44, v195
	ds_write_b16 v51, v44 offset:272
	v_mul_f32_e32 v54, v64, v54
	v_cvt_pk_bf16_f32 v44, v54, v195
	ds_write_b16 v51, v44 offset:4624
	v_mul_f32_e32 v44, 0x3fb8aa3b, v37
	v_exp_f32_e32 v44, v44
	v_min_f32_e64 v54, -v37, s31
	v_mul_f32_e32 v54, 0x3fb8aa3b, v54
	v_exp_f32_e32 v54, v54
	v_mul_f32_e32 v44, v44, v60
	v_cvt_pk_bf16_f32 v44, v44, v195
	ds_write_b16 v51, v44 offset:544
	v_mul_f32_e32 v54, v63, v54
	v_cvt_pk_bf16_f32 v44, v54, v195
	ds_write_b16 v51, v44 offset:4896
	v_add_f32_e32 v44, v59, v45
	v_sub_f32_e32 v42, v36, v42
	v_sub_f32_e32 v43, v36, v43
	v_mul_f32_e32 v45, 0x3fb8aa3b, v44
	v_mul_f32_e32 v42, 0x3fb8aa3b, v42
	v_mul_f32_e32 v43, 0x3fb8aa3b, v43
	v_sub_f32_e32 v37, v36, v37
	v_exp_f32_e32 v45, v45
	v_min_f32_e64 v54, -v44, s31
	v_sub_f32_e32 v44, v36, v44
	v_exp_f32_e32 v42, v42
	v_exp_f32_e32 v43, v43
	v_mul_f32_e32 v37, 0x3fb8aa3b, v37
	v_mul_f32_e32 v54, 0x3fb8aa3b, v54
	v_mul_f32_e32 v44, 0x3fb8aa3b, v44
	v_exp_f32_e32 v37, v37
	v_exp_f32_e32 v54, v54
	v_exp_f32_e32 v44, v44
	v_mul_f32_e32 v45, v45, v55
	v_mul_f32_e32 v42, v56, v42
	v_mul_f32_e32 v43, v64, v43
	v_cvt_pk_bf16_f32 v45, v45, v195
	v_mul_f32_e32 v37, v63, v37
	v_mul_f32_e32 v54, v53, v54
	v_mul_f32_e32 v44, v53, v44
	ds_write_b16 v51, v45 offset:816
	v_cvt_pk_bf16_f32 v45, v54, v195
	ds_write_b16 v51, v45 offset:5168
	v_cvt_pk_bf16_f32 v42, v42, v43
	v_cvt_pk_bf16_f32 v43, v37, v44
	ds_write_b64 v52, v[42:43] offset:8704
	s_and_saveexec_b64 s[2:3], s[38:39]
	s_cbranch_execz .LBB0_235
	v_mul_f32_e32 v37, 0x3fb8aa3b, v36
	v_exp_f32_e32 v37, v37
	ds_write_b32 v49, v37 offset:18944

; #define LAS __attribute__((address_space(3)))
; __device__ __forceinline__ unsigned cvt_pk_bf16(float lo, float hi) { unsigned r; asm volatile("v_cvt_pk_bf16_f32 %0, %1, %2" : "=v"(r) : "v"(lo), "v"(hi)); return r; }
; __device__ __forceinline__ float bf2f(unsigned short b) { return __uint_as_float(((unsigned)b) << 16); }
; template <bool FULL>
; __device__ __forceinline__ void hgrn_item(LAS unsigned char* lds, const bf16_t* P, bf16_t* AB, int L, int hd, const float* lbv, const float* anorm, const float* S0, const float* Dd, int ns, float* Sout, float* Dout) {
;     ...
;     const bf16_t* pq = P + 128 * hd + k + (size_t)(4 * tq) * N1;
;     const bf16_t* pz = pq + 512;
;     const int vt = (tid >> 4) & 15, vc = tid & 15;
;     const bf16_t* pv = P + 1024 + 128 * hd + 8 * vc + (size_t)vt * N1;
;     const bf16_t* pg = P + 1536 + 128 * hd + 16 * w + c16 + (size_t)(4 * q4) * N1;
;     bf16_t* po = AB + 128 * hd + 16 * w + c16 + (size_t)(4 * q4) * D;
;     const int nsteps = L >> 4;
;     float btot = 0.f;
;     unsigned short zr[4], qr[4], grn[4]; u32x4 vr = (u32x4){0u, 0u, 0u, 0u};
; #pragma unroll
;     for (int i = 0; i < 4; ++i) { zr[i] = pz[(size_t)i * N1]; qr[i] = pq[(size_t)i * N1]; grn[i] = pg[(size_t)i * N1]; }
;     if (tid < 256) vr = *(const u32x4*)pv;
;     ...
;         if (FULL) {
;             f32x4 tot = (f32x4){0.f, 0.f, 0.f, 0.f};
; #pragma unroll
;             for (int ww = 0; ww < 8; ++ww) tot += *(const LAS f32x4*)(ssq + ww * 16 + 4 * q4);
; #pragma unroll
;             for (int j = 0; j < 4; ++j) { const float rstd = __builtin_amdgcn_rsqf(tot[j] * (1.f / 128.f) + EPS); const float o = acco[j] * rstd * an * bf2f(gr[j]);
;                 po[(size_t)(16 * n + j) * D] = (bf16_t)(cvt_pk_bf16(o, 0.f) & 0xffffu); }
.LBB0_329:
	s_or_b64 exec, exec, s[0:1]
	s_movk_i32 s0, 0x80
	v_lshl_add_u32 v92, v50, 2, 0
	v_cmp_gt_u32_e64 s[36:37], s0, v50
	v_mul_u32_u24_e32 v50, 40, v51
	v_lshlrev_b32_e32 v49, 1, v49
	v_add3_u32 v94, 0, v50, v49
	v_mul_lo_u32 v50, v52, 40
	v_lshlrev_b32_e32 v49, 2, v72
	v_lshlrev_b32_e32 v52, 2, v34
	s_movk_i32 s0, 0x220
	v_lshlrev_b64 v[32:33], 11, v[32:33]
	v_lshl_add_u32 v93, v48, 2, 0
	v_mul_u32_u24_e32 v54, 40, v48
	v_add3_u32 v95, 0, v49, v52
	v_mad_u64_u32 v[48:49], s[0:1], v35, s0, v[48:49]
	v_lshlrev_b32_e32 v90, 1, v34
	v_cmp_lt_i32_e64 s[40:41], 0, v35
	v_cmp_lt_i32_e64 s[42:43], 1, v35
	v_cmp_lt_i32_e64 s[44:45], 2, v35
	v_cmp_lt_i32_e64 s[46:47], 3, v35
	v_cmp_lt_u32_e64 s[48:49], v84, v34
	v_cmp_gt_u32_e64 s[50:51], v84, v34
	v_or_b32_e32 v35, 2, v34
	v_or_b32_e32 v34, 3, v34
	v_lshl_add_u64 v[32:33], v[72:73], 1, v[32:33]
	v_readlane_b32 s0, v248, 7
	v_add_u32_e32 v91, 0, v90
	v_cmp_lt_u32_e64 s[54:55], v84, v34
	v_mul_u32_u24_e32 v34, 40, v84
	v_lshl_add_u64 v[32:33], v[32:33], 0, v[194:195]
	v_readlane_b32 s1, v248, 8
	v_lshl_add_u32 v53, v53, 1, 0
	v_mul_u32_u24_e32 v51, 0x88, v84
	v_cmp_lt_u32_e64 s[52:53], v84, v35
	v_lshl_add_u64 v[80:81], s[0:1], 0, v[32:33]
	v_add_u32_e32 v100, v91, v34
	s_waitcnt vmcnt(0)
	v_mov_b64_e32 v[32:33], v[36:37]
	v_sub_f32_e32 v89, 1.0, v103
	s_mov_b32 s2, 0
	v_cmp_eq_u32_e64 s[38:39], 0, v84
	v_lshl_add_u32 v96, v48, 1, 0
	v_lshl_add_u32 v97, v51, 1, v91
	v_add_u32_e32 v98, v53, v54
	v_add_u32_e32 v99, v91, v50
	v_mov_b64_e32 v[34:35], v[38:39]
	s_mov_b32 s99, 0x42e6d4ca
	s_branch .LBB0_331
.LBB0_330:
	s_or_b64 exec, exec, s[0:1]
	s_waitcnt lgkmcnt(0)
	s_barrier
	ds_read_b128 v[40:43], v116 offset:21504
	ds_read_b128 v[128:131], v116 offset:21568
	ds_read_b128 v[132:135], v116 offset:21632
	ds_read_b128 v[136:139], v116 offset:21696
	ds_read_b128 v[140:143], v116 offset:21760
	ds_read_b128 v[144:147], v116 offset:21824
	ds_read_b128 v[148:151], v116 offset:21888
	ds_read_b128 v[152:155], v116 offset:21952
	s_cmp_eq_u32 s2, 32
	s_waitcnt lgkmcnt(4)
	v_pk_add_f32 v[44:45], v[42:43], 0 op_sel_hi:[1,0]
	v_pk_add_f32 v[46:47], v[40:41], 0 op_sel_hi:[1,0]
	v_pk_add_f32 v[44:45], v[44:45], v[130:131]
	v_pk_add_f32 v[46:47], v[46:47], v[128:129]
	v_pk_add_f32 v[44:45], v[44:45], v[134:135]
	v_pk_add_f32 v[46:47], v[46:47], v[132:133]
	v_pk_add_f32 v[44:45], v[44:45], v[138:139]
	v_pk_add_f32 v[46:47], v[46:47], v[136:137]
	s_waitcnt lgkmcnt(0)
	v_pk_add_f32 v[44:45], v[44:45], v[142:143]
	v_pk_add_f32 v[46:47], v[46:47], v[140:141]
	v_pk_add_f32 v[44:45], v[44:45], v[146:147]
	v_pk_add_f32 v[46:47], v[46:47], v[144:145]
	v_pk_add_f32 v[44:45], v[44:45], v[150:151]
	v_pk_add_f32 v[46:47], v[46:47], v[148:149]
	v_pk_add_f32 v[40:41], v[46:47], v[152:153]
	s_nop 0
	v_fmamk_f32 v40, v40, 0x3c000000, v193
	v_rsq_f32_e32 v40, v40
	v_pk_add_f32 v[42:43], v[44:45], v[154:155]
	v_add_co_u32_e64 v44, s[0:1], s68, v80
	v_mul_f32_e32 v36, v36, v40
	v_mul_f32_e32 v36, v104, v36
	v_lshlrev_b32_e32 v40, 16, v85
	v_mul_f32_e32 v36, v36, v40
	v_cvt_pk_bf16_f32 v36, v36, v195
	v_addc_co_u32_e64 v45, s[0:1], -1, v81, s[0:1]
	global_store_short v[44:45], v36, off offset:-2048
	v_fmamk_f32 v36, v41, 0x3c000000, v193
	v_rsq_f32_e32 v36, v36
	s_mov_b64 s[0:1], 0x8000
	s_waitcnt vmcnt(10)
	v_mov_b32_e32 v85, v107
	v_mov_b32_e32 v46, v105
	v_mul_f32_e32 v36, v37, v36
	v_mul_f32_e32 v36, v104, v36
	v_lshlrev_b32_e32 v37, 16, v86
	v_mul_f32_e32 v36, v36, v37
	v_cvt_pk_bf16_f32 v36, v36, v195
	global_store_short v[80:81], v36, off offset:-4096
	v_fmamk_f32 v36, v42, 0x3c000000, v193
	v_rsq_f32_e32 v36, v36
	v_lshlrev_b32_e32 v37, 16, v87
	s_waitcnt vmcnt(8)
	v_mov_b32_e32 v86, v109
	s_waitcnt vmcnt(5)
	v_mov_b32_e32 v87, v113
	v_mul_f32_e32 v36, v38, v36
	v_mul_f32_e32 v36, v104, v36
	v_mul_f32_e32 v36, v36, v37
	v_cvt_pk_bf16_f32 v36, v36, v195
	global_store_short v[80:81], v36, off offset:-2048
	v_fmamk_f32 v36, v43, 0x3c000000, v193
	v_rsq_f32_e32 v36, v36
	v_lshlrev_b32_e32 v37, 16, v88
	s_waitcnt vmcnt(3)
	v_mov_b32_e32 v88, v115
	v_mov_b32_e32 v41, v108
	v_mul_f32_e32 v36, v39, v36
	v_mul_f32_e32 v36, v104, v36
	v_mul_f32_e32 v36, v36, v37
	v_cvt_pk_bf16_f32 v36, v36, v195
	global_store_short v[80:81], v36, off
	v_mov_b64_e32 v[38:39], v[34:35]
	v_lshl_add_u64 v[80:81], v[80:81], 0, s[0:1]
	v_mov_b32_e32 v43, v111
	v_mov_b32_e32 v40, v114
	v_mov_b32_e32 v47, v101
	v_mov_b32_e32 v45, v106
	v_mov_b32_e32 v44, v110
	v_mov_b32_e32 v42, v112
	v_mov_b64_e32 v[36:37], v[32:33]
	s_cbranch_scc1 .LBB0_339

; #define LAS __attribute__((address_space(3)))
; __device__ __forceinline__ unsigned cvt_pk_bf16(float lo, float hi) { unsigned r; asm volatile("v_cvt_pk_bf16_f32 %0, %1, %2" : "=v"(r) : "v"(lo), "v"(hi)); return r; }
; __device__ __forceinline__ float bf2f(unsigned short b) { return __uint_as_float(((unsigned)b) << 16); }
; template <bool FULL>
; __device__ __forceinline__ void hgrn_item(LAS unsigned char* lds, const bf16_t* P, bf16_t* AB, int L, int hd, const float* lbv, const float* anorm, const float* S0, const float* Dd, int ns, float* Sout, float* Dout) {
;     ...
;         {
;             float run = 0.f;
; #pragma unroll
;             for (int i = 0; i < 4; ++i) { float z = bf2f(zc[i]); z = fminf(fmaxf(z, -30.f), 30.f); const float e = __expf(-z), sg = __builtin_amdgcn_rcpf(1.f + e), sn = e * sg;
;                 const float f = lb + oml * sg; run += __builtin_amdgcn_logf(f) * 0.69314718056f; cs[i] = run; kk[i] = oml * sn; qv[i] = bf2f(qc[i]); }
;             qsum[tq * 128 + k] = run;
;         }
;         __syncthreads();
;         {
;             float pre = 0.f, tot = 0.f;
; #pragma unroll
;             for (int j = 0; j < 4; ++j) { const float v = qsum[j * 128 + k]; tot += v; pre += (j < tq) ? v : 0.f; }
;             btot += tot;
;             float kh[4];
; #pragma unroll
;             for (int i = 0; i < 4; ++i) { const float b = pre + cs[i]; const float qt = qv[i] * __expf(b), kt = kk[i] * __expf(fminf(-b, 80.f)); kh[i] = kk[i] * __expf(tot - b);
;                 Qt[(4 * tq + i) * 136 + k] = (bf16_t)(cvt_pk_bf16(qt, 0.f) & 0xffffu); Kt[(4 * tq + i) * 136 + k] = (bf16_t)(cvt_pk_bf16(kt, 0.f) & 0xffffu); }
;             u32x2 kp; kp.x = cvt_pk_bf16(kh[0], kh[1]); kp.y = cvt_pk_bf16(kh[2], kh[3]);
;             *(LAS u32x2*)(KhT + k * 20 + 4 * tq) = kp;
;             if (tq == 0) dvec[k] = __expf(tot);
.LBB0_333:
	s_or_b64 exec, exec, s[0:1]
	v_lshlrev_b32_e32 v51, 16, v41
	v_lshlrev_b32_e32 v41, 16, v44
	v_max_f32_e32 v41, v41, v41
	v_med3_f32 v41, v41, s29, v225
	v_mul_f32_e32 v41, 0xbfb8aa3b, v41
	v_exp_f32_e32 v41, v41
	v_lshlrev_b32_e32 v47, 16, v47
	v_max_f32_e32 v47, v47, v47
	v_lshlrev_b32_e32 v45, 16, v45
	v_add_f32_e32 v44, 1.0, v41
	v_rcp_f32_e32 v44, v44
	v_med3_f32 v47, v47, s29, v225
	v_max_f32_e32 v45, v45, v45
	v_mul_f32_e32 v47, 0xbfb8aa3b, v47
	v_mul_f32_e32 v41, v41, v44
	v_med3_f32 v45, v45, s29, v225
	v_mul_f32_e32 v52, v89, v41
	v_lshlrev_b32_e32 v41, 16, v42
	v_exp_f32_e32 v47, v47
	v_mul_f32_e32 v45, 0xbfb8aa3b, v45
	v_max_f32_e32 v41, v41, v41
	v_exp_f32_e32 v45, v45
	v_med3_f32 v41, v41, s29, v225
	v_mul_f32_e32 v41, 0xbfb8aa3b, v41
	v_exp_f32_e32 v41, v41
	v_add_f32_e32 v48, 1.0, v47
	v_rcp_f32_e32 v48, v48
	v_add_f32_e32 v49, 1.0, v45
	v_rcp_f32_e32 v49, v49
	v_add_f32_e32 v42, 1.0, v41
	v_rcp_f32_e32 v42, v42
	v_mul_f32_e32 v47, v47, v48
	v_fma_f32 v48, v89, v48, v103
	v_log_f32_e32 v48, v48
	v_mul_f32_e32 v45, v45, v49
	v_fma_f32 v49, v89, v49, v103
	v_log_f32_e32 v49, v49
	v_fma_f32 v44, v89, v44, v103
	v_log_f32_e32 v44, v44
	v_mul_f32_e32 v41, v41, v42
	v_fma_f32 v42, v89, v42, v103
	v_log_f32_e32 v42, v42
	v_add_f32_e32 v49, v49, v48
	v_mul_f32_e32 v54, v89, v41
	v_add_f32_e32 v41, v44, v49
	v_add_f32_e32 v56, v42, v41
	v_lshlrev_b32_e32 v53, 16, v43
	ds_write_b32 v92, v56 offset:19456
	s_waitcnt lgkmcnt(0)
	s_barrier
	ds_read2st64_b32 v[42:43], v93 offset0:76 offset1:78
	ds_read2st64_b32 v[128:129], v93 offset0:80 offset1:82
	v_lshlrev_b32_e32 v55, 16, v40
	v_mul_f32_e32 v50, v89, v45
	v_lshlrev_b32_e32 v46, 16, v46
	v_mul_f32_e32 v47, v89, v47
	s_waitcnt lgkmcnt(1)
	v_add_f32_e32 v40, 0, v42
	v_cndmask_b32_e64 v42, 0, v40, s[40:41]
	v_add_f32_e32 v40, v40, v43
	v_cndmask_b32_e64 v43, 0, v43, s[42:43]
	v_add_f32_e32 v44, v42, v43
	s_waitcnt lgkmcnt(0)
	v_mov_b32_e32 v42, v128
	v_mov_b32_e32 v43, v129
	v_add_f32_e32 v40, v40, v42
	v_cndmask_b32_e64 v42, 0, v42, s[44:45]
	v_add_f32_e32 v42, v44, v42
	v_cndmask_b32_e64 v44, 0, v43, s[46:47]
	v_add_f32_e32 v45, v42, v44
	v_add_f32_e32 v42, v48, v45
	v_exp_f32_e32 v44, v42
	s_nop 0
	v_mul_f32_e32 v46, v44, v46
	v_min_f32_e64 v44, -v42, s99
	v_exp_f32_e32 v44, v44
	s_nop 0
	v_mul_f32_e32 v48, v47, v44
	v_mov_b32_e32 v44, v43
	v_cvt_pk_bf16_f32 v43, v46, v195
	ds_write_b16 v96, v43
	v_cvt_pk_bf16_f32 v43, v48, v195
	ds_write_b16 v96, v43 offset:4352
	v_add_f32_e32 v43, v49, v45
	v_pk_add_f32 v[40:41], v[40:41], v[44:45]
	v_exp_f32_e32 v44, v43
	v_min_f32_e64 v46, -v43, s99
	v_exp_f32_e32 v46, v46
	v_mul_f32_e32 v44, v44, v51
	v_cvt_pk_bf16_f32 v44, v44, v195
	ds_write_b16 v96, v44 offset:272
	v_mul_f32_e32 v46, v50, v46
	v_cvt_pk_bf16_f32 v44, v46, v195
	ds_write_b16 v96, v44 offset:4624
	v_exp_f32_e32 v44, v41
	v_min_f32_e64 v46, -v41, s99
	v_exp_f32_e32 v46, v46
	v_mul_f32_e32 v44, v44, v53
	v_cvt_pk_bf16_f32 v44, v44, v195
	ds_write_b16 v96, v44 offset:544
	v_mul_f32_e32 v46, v52, v46
	v_cvt_pk_bf16_f32 v44, v46, v195
	ds_write_b16 v96, v44 offset:4896
	v_add_f32_e32 v44, v56, v45
	v_sub_f32_e32 v42, v40, v42
	v_sub_f32_e32 v43, v40, v43
	v_sub_f32_e32 v41, v40, v41
	v_exp_f32_e32 v45, v44
	v_min_f32_e64 v46, -v44, s99
	v_sub_f32_e32 v44, v40, v44
	v_exp_f32_e32 v42, v42
	v_exp_f32_e32 v43, v43
	v_exp_f32_e32 v41, v41
	v_exp_f32_e32 v46, v46
	v_exp_f32_e32 v44, v44
	v_mul_f32_e32 v45, v45, v55
	v_mul_f32_e32 v42, v47, v42
	v_mul_f32_e32 v43, v50, v43
	v_cvt_pk_bf16_f32 v45, v45, v195
	v_mul_f32_e32 v41, v52, v41
	v_mul_f32_e32 v46, v54, v46
	v_mul_f32_e32 v44, v54, v44
	ds_write_b16 v96, v45 offset:816
	v_cvt_pk_bf16_f32 v45, v46, v195
	ds_write_b16 v96, v45 offset:5168
	v_cvt_pk_bf16_f32 v42, v42, v43
	v_cvt_pk_bf16_f32 v43, v41, v44
	ds_write_b64 v98, v[42:43] offset:8704
	s_and_saveexec_b64 s[0:1], s[36:37]
	s_cbranch_execz .LBB0_335
	v_exp_f32_e32 v40, v40
	ds_write_b32 v93, v40 offset:18944

; #define LAS __attribute__((address_space(3)))
; template <bool FULL>
; __device__ __forceinline__ void hgrn_item(LAS unsigned char* lds, const bf16_t* P, bf16_t* AB, int L, int hd, const float* lbv, const float* anorm, const float* S0, const float* Dd, int ns, float* Sout, float* Dout) {
;     ...
;         f32x4 acco = (f32x4){0.f, 0.f, 0.f, 0.f};
;         {
;             const u32x2 vv = *(const LAS u32x2*)(VsT + (16 * w + c16) * 20 + 4 * q4);
;             const bf16x4 vf = __builtin_bit_cast(bf16x4, vv);
;             if (FULL) {
;             bf16x8 qf[4], kf[4];
; #pragma unroll
;             for (int kq = 0; kq < 4; ++kq) {
;                 const u32x2 a0 = *(const LAS u32x2*)(Qt + c16 * 136 + 32 * kq + 4 * q4), a1 = *(const LAS u32x2*)(Qt + c16 * 136 + 32 * kq + 16 + 4 * q4);
;                 const u32x2 b0 = *(const LAS u32x2*)(Kt + c16 * 136 + 32 * kq + 4 * q4), b1 = *(const LAS u32x2*)(Kt + c16 * 136 + 32 * kq + 16 + 4 * q4);
;                 u32x4 qa = (u32x4){a0.x, a0.y, a1.x, a1.y}, ka = (u32x4){b0.x, b0.y, b1.x, b1.y};
;                 qf[kq] = __builtin_bit_cast(bf16x8, qa); kf[kq] = __builtin_bit_cast(bf16x8, ka);
;             }
;             f32x4 accA = (f32x4){0.f, 0.f, 0.f, 0.f};
; #pragma unroll
;             for (int kq = 0; kq < 4; ++kq) accA = __builtin_amdgcn_mfma_f32_16x16x32_bf16(kf[kq], qf[kq], accA, 0, 0, 0);
; #pragma unroll
;             for (int j = 0; j < 4; ++j) accA[j] = (c16 >= 4 * q4 + j) ? accA[j] : 0.f;
;             u32x2 pa; pa.x = cvt_pk_bf16(accA[0], accA[1]); pa.y = cvt_pk_bf16(accA[2], accA[3]);
;             const bf16x4 pA = __builtin_bit_cast(bf16x4, pa);
;             acco = __builtin_amdgcn_mfma_f32_16x16x16bf16_1k(pA, vf, (f32x4){0.f, 0.f, 0.f, 0.f}, 0, 0, 0);
; #pragma unroll
;             for (int kq = 0; kq < 4; ++kq) {
;                 u32x4 sp; sp.x = cvt_pk_bf16(accS[2 * kq][0], accS[2 * kq][1]); sp.y = cvt_pk_bf16(accS[2 * kq][2], accS[2 * kq][3]);
;                 sp.z = cvt_pk_bf16(accS[2 * kq + 1][0], accS[2 * kq + 1][1]); sp.w = cvt_pk_bf16(accS[2 * kq + 1][2], accS[2 * kq + 1][3]);
;                 acco = __builtin_amdgcn_mfma_f32_16x16x32_bf16(qf[kq], __builtin_bit_cast(bf16x8, sp), acco, 0, 0, 0);
;             }
;             }
; #pragma unroll
;             for (int mt = 0; mt < 8; ++mt) {
;                 const u32x2 kh2 = *(const LAS u32x2*)(KhT + (16 * mt + c16) * 20 + 4 * q4);
.LBB0_337:
	s_or_b64 exec, exec, s[0:1]
	s_waitcnt lgkmcnt(0)
	s_barrier
	ds_read_b64 v[82:83], v99 offset:13824
	ds_read2_b64 v[36:39], v97 offset1:4
	v_add_u32_e32 v64, 0x1000, v97
	ds_read2_b64 v[52:55], v64 offset0:32 offset1:36
	ds_read2_b64 v[40:43], v97 offset0:8 offset1:12
	ds_read2_b64 v[56:59], v64 offset0:40 offset1:44
	ds_read2_b64 v[44:47], v97 offset0:16 offset1:20
	ds_read2_b64 v[60:63], v64 offset0:48 offset1:52
	ds_read2_b64 v[48:51], v97 offset0:24 offset1:28
	ds_read2_b64 v[64:67], v64 offset0:56 offset1:60
	v_add_u32_e32 v116, v91, v90
	v_add_u32_e32 v208, 0x2000, v100
	v_add_u32_e32 v209, 0x2400, v100
	ds_read_b128 v[156:159], v116 offset:18944
	ds_read_b128 v[160:163], v116 offset:19008
	ds_read2_b64 v[118:121], v208 offset0:64 offset1:144
	ds_read_b128 v[164:167], v116 offset:19072
	ds_read_b128 v[168:171], v116 offset:19136
	ds_read2_b64 v[196:199], v209 offset0:96 offset1:176
	s_waitcnt lgkmcnt(12)
	v_mfma_f32_16x16x32_bf16 v[52:55], v[52:55], v[36:39], 0
	v_add_u32_e32 v210, 0x2800, v100
	v_add_u32_e32 v211, 0x3000, v100
	s_waitcnt lgkmcnt(10)
	v_mfma_f32_16x16x32_bf16 v[52:55], v[56:59], v[40:43], v[52:55]
	s_waitcnt lgkmcnt(8)
	v_mfma_f32_16x16x32_bf16 v[52:55], v[60:63], v[44:47], v[52:55]
	s_waitcnt lgkmcnt(6)
	v_mfma_f32_16x16x32_bf16 v[52:55], v[64:67], v[48:51], v[52:55]
	ds_read_b128 v[172:175], v116 offset:19200
	ds_read_b128 v[176:179], v116 offset:19264
	ds_read2_b64 v[200:203], v210 offset0:128 offset1:208
	ds_read_b128 v[180:183], v116 offset:19328
	ds_read_b128 v[184:187], v116 offset:19392
	ds_read2_b64 v[204:207], v211 offset0:32 offset1:112
	s_nop 3
	v_cndmask_b32_e64 v52, v52, 0, s[48:49]
	v_cndmask_b32_e64 v53, 0, v53, s[50:51]
	v_cndmask_b32_e64 v54, v54, 0, s[52:53]
	v_cndmask_b32_e64 v55, v55, 0, s[54:55]
	v_cvt_pk_bf16_f32 v52, v52, v53
	v_cvt_pk_bf16_f32 v53, v54, v55
	v_cvt_pk_bf16_f32 v56, v24, v25
	v_cvt_pk_bf16_f32 v57, v26, v27
	v_cvt_pk_bf16_f32 v58, v28, v29
	v_cvt_pk_bf16_f32 v59, v30, v31
	v_cvt_pk_bf16_f32 v60, v20, v21
	v_cvt_pk_bf16_f32 v61, v22, v23
	v_cvt_pk_bf16_f32 v62, v16, v17
	v_cvt_pk_bf16_f32 v63, v18, v19
	v_cvt_pk_bf16_f32 v64, v12, v13
	v_cvt_pk_bf16_f32 v65, v14, v15
	v_cvt_pk_bf16_f32 v66, v8, v9
	v_cvt_pk_bf16_f32 v67, v10, v11
	v_cvt_pk_bf16_f32 v68, v4, v5
	v_cvt_pk_bf16_f32 v69, v6, v7
	v_cvt_pk_bf16_f32 v70, v0, v1
	v_cvt_pk_bf16_f32 v71, v2, v3
	v_mfma_f32_16x16x16_bf16 v[52:55], v[52:53], v[82:83], 0
	s_waitcnt lgkmcnt(6)
	v_pk_mul_f32 v[24:25], v[24:25], v[156:157]
	v_pk_mul_f32 v[26:27], v[26:27], v[158:159]
	v_mfma_f32_16x16x32_bf16 v[36:39], v[36:39], v[56:59], v[52:55]
	v_pk_mul_f32 v[28:29], v[28:29], v[160:161]
	v_pk_mul_f32 v[30:31], v[30:31], v[162:163]
	v_mfma_f32_16x16x16_bf16 v[24:27], v[118:119], v[82:83], v[24:27]
	s_nop 0
	v_mfma_f32_16x16x16_bf16 v[28:31], v[120:121], v[82:83], v[28:31]
	v_pk_mul_f32 v[20:21], v[20:21], v[164:165]
	v_pk_mul_f32 v[22:23], v[22:23], v[166:167]
	v_mfma_f32_16x16x32_bf16 v[36:39], v[40:43], v[60:63], v[36:39]
	v_pk_mul_f32 v[16:17], v[16:17], v[168:169]
	v_pk_mul_f32 v[18:19], v[18:19], v[170:171]
	v_mfma_f32_16x16x16_bf16 v[20:23], v[196:197], v[82:83], v[20:23]
	s_nop 0
	v_mfma_f32_16x16x16_bf16 v[16:19], v[198:199], v[82:83], v[16:19]
	s_waitcnt lgkmcnt(3)
	v_pk_mul_f32 v[12:13], v[12:13], v[172:173]
	v_pk_mul_f32 v[14:15], v[14:15], v[174:175]
	v_mfma_f32_16x16x32_bf16 v[36:39], v[44:47], v[64:67], v[36:39]
	v_pk_mul_f32 v[8:9], v[8:9], v[176:177]
	v_pk_mul_f32 v[10:11], v[10:11], v[178:179]
	v_mfma_f32_16x16x16_bf16 v[12:15], v[200:201], v[82:83], v[12:15]
	s_nop 0
	v_mfma_f32_16x16x16_bf16 v[8:11], v[202:203], v[82:83], v[8:11]
	s_waitcnt lgkmcnt(0)
	v_pk_mul_f32 v[4:5], v[4:5], v[180:181]
	v_mfma_f32_16x16x32_bf16 v[36:39], v[48:51], v[68:71], v[36:39]
	v_mul_f32_e64 v6, v6, v182
	v_mul_f32_e64 v7, v7, v183
	v_pk_mul_f32 v[0:1], v[0:1], v[184:185]
	v_pk_mul_f32 v[2:3], v[2:3], v[186:187]
	s_nop 3
	v_pk_mul_f32 v[44:45], v[38:39], v[38:39]
	v_pk_mul_f32 v[42:43], v[36:37], v[36:37]
	v_mfma_f32_16x16x16_bf16 v[4:7], v[204:205], v[82:83], v[4:7]
	v_add_f32_dpp v44, v44, v44 row_ror:8 row_mask:0xf bank_mask:0xf bound_ctrl:1
	v_add_f32_dpp v45, v45, v45 row_ror:8 row_mask:0xf bank_mask:0xf bound_ctrl:1
	v_add_f32_dpp v42, v42, v42 row_ror:8 row_mask:0xf bank_mask:0xf bound_ctrl:1
	v_add_f32_dpp v43, v43, v43 row_ror:8 row_mask:0xf bank_mask:0xf bound_ctrl:1
	v_mfma_f32_16x16x16_bf16 v[0:3], v[206:207], v[82:83], v[0:3]
	v_add_f32_dpp v44, v44, v44 row_ror:4 row_mask:0xf bank_mask:0xf bound_ctrl:1
	v_add_f32_dpp v45, v45, v45 row_ror:4 row_mask:0xf bank_mask:0xf bound_ctrl:1
	v_add_f32_dpp v42, v42, v42 row_ror:4 row_mask:0xf bank_mask:0xf bound_ctrl:1
	v_add_f32_dpp v43, v43, v43 row_ror:4 row_mask:0xf bank_mask:0xf bound_ctrl:1
	v_add_f32_dpp v44, v44, v44 row_ror:2 row_mask:0xf bank_mask:0xf bound_ctrl:1
	v_add_f32_dpp v45, v45, v45 row_ror:2 row_mask:0xf bank_mask:0xf bound_ctrl:1
	v_add_f32_dpp v42, v42, v42 row_ror:2 row_mask:0xf bank_mask:0xf bound_ctrl:1
	v_add_f32_dpp v43, v43, v43 row_ror:2 row_mask:0xf bank_mask:0xf bound_ctrl:1
	v_add_f32_dpp v44, v44, v44 row_ror:1 row_mask:0xf bank_mask:0xf bound_ctrl:1
	v_add_f32_dpp v45, v45, v45 row_ror:1 row_mask:0xf bank_mask:0xf bound_ctrl:1
	v_add_f32_dpp v42, v42, v42 row_ror:1 row_mask:0xf bank_mask:0xf bound_ctrl:1
	v_add_f32_dpp v43, v43, v43 row_ror:1 row_mask:0xf bank_mask:0xf bound_ctrl:1
	s_and_saveexec_b64 s[0:1], s[38:39]
	s_cbranch_execz .LBB0_330
	ds_write_b128 v95, v[42:45] offset:21504
	s_branch .LBB0_330
